# retention chunk scan: in the four odd steps the staged state-tile read goes to spare registers and its global store moves after the first MFMA, removing an lgkmcnt(0) round trip between the step barri
# speedup vs baseline: 1.0043x; 1.0043x over previous
; #define LAS __attribute__((address_space(3)))
; __device__ __forceinline__ unsigned pk2(float lo, float hi) { const f32x2 v = {lo, hi}; const bf16x2_t b = __builtin_convertvector(v, bf16x2_t); return __builtin_bit_cast(unsigned, b); }
; __device__ __forceinline__ void ret_scan_phase(int j, LAS unsigned char* lds, int tid, int lane, int wave) { KARGS;
;     ...
;                 if (samp ? (s > 0) : (s & 1)) { const int sbp = samp ? ((s - 1) & 1) : (((s - 1) >> 1) & 1);
;                   const u32x4 vv = *(const LAS u32x4*)(lds + 2 * RS_STAGE + sbp * RS_TILE + (tid >> 3) * RS_PITCH + (tid & 7) * 16);
;                   *(u32x4*)(ST + ((size_t)((c - 1) * 8 + h) * 512 + 64 * eo + (tid >> 3)) * 256 + 64 * dq + (tid & 7) * 8) = vv; }
;                 if (samp || !(s & 1)) { const int sb = samp ? (s & 1) : ((s >> 1) & 1);
;                   LAS unsigned char* sp = lds + 2 * RS_STAGE + sb * RS_TILE + (32 * ep + fr) * RS_PITCH + (16 * dtw + 4 * fq) * 2;
;                   u32x2 p; p.x = pk2(acc0[0], acc0[1]); p.y = pk2(acc0[2], acc0[3]); *(LAS u32x2*)sp = p;
;                   p.x = pk2(acc1[0], acc1[1]); p.y = pk2(acc1[2], acc1[3]); *(LAS u32x2*)(sp + 16 * RS_PITCH) = p; }
;                 acc0 *= g64; acc1 *= g64;
;                 { const LAS unsigned char* st = lds + (c & 1) * RS_STAGE;
; #pragma unroll
;                   for (int ks = 0; ks < 2; ++ks) { const bf16x8 kf = *(const LAS bf16x8*)(st + ka_off + 64 * ks), v0 = *(const LAS bf16x8*)(st + vb_off + 64 * ks), v1 = *(const LAS bf16x8*)(st + vb_off + 16 * RS_PITCH + 64 * ks);
;                       acc0 = __builtin_amdgcn_mfma_f32_16x16x32_bf16(kf, v0, acc0, 0, 0, 0); acc1 = __builtin_amdgcn_mfma_f32_16x16x32_bf16(kf, v1, acc1, 0, 0, 0); } }
.LBB0_658:
	s_add_i32 s8, s71, 9
	s_min_u32 s8, s8, 0x7e
	s_add_i32 s8, s8, 9
	s_lshl_b32 s68, s8, 18
	s_barrier
	ds_write_b128 v164, v[72:75]
	ds_write_b128 v164, v[80:83] offset:9216
	v_lshl_add_u64 v[72:73], v[154:155], 0, s[68:69]
	s_lshl_b32 s68, s8, 19
	v_lshl_add_u64 v[80:81], v[156:157], 0, s[68:69]
	global_load_dwordx4 v[72:75], v[72:73], off
	ds_read_b128 v[180:183], v164 offset:36864
	global_load_dwordx4 v[80:83], v[80:81], off
	v_cndmask_b32_e64 v159, 0, 1, s[6:7]
	v_lshl_add_u64 v[184:185], v[146:147], 0, s[4:5]
	v_cmp_ne_u32_e64 s[8:9], 1, v159
	s_andn2_b64 vcc, exec, s[6:7]
	s_cbranch_vccnz .LBB0_660
	s_nop 0
	v_cvt_pk_bf16_f32 v168, v128, v129
	v_cvt_pk_bf16_f32 v169, v130, v131
	ds_write_b64 v166, v[168:169] offset:46080
	v_cvt_pk_bf16_f32 v168, v132, v133
	v_cvt_pk_bf16_f32 v169, v134, v135
	ds_write_b64 v166, v[168:169] offset:48384
.LBB0_660:
	ds_read_b128 v[168:171], v167 offset:18432
	ds_read_b128 v[172:175], v145 offset:27648
	ds_read_b128 v[176:179], v145 offset:29952
	v_mov_b32_e32 v159, v158
	v_pk_mul_f32 v[130:131], v[158:159], v[130:131]
	v_pk_mul_f32 v[128:129], v[160:161], v[128:129]
	v_pk_mul_f32 v[134:135], v[158:159], v[134:135]
	v_pk_mul_f32 v[132:133], v[160:161], v[132:133]
	s_waitcnt lgkmcnt(1)
	v_mfma_f32_16x16x32_bf16 v[128:131], v[168:171], v[172:175], v[128:131]
	global_store_dwordx4 v[184:185], v[180:183], off
	v_cndmask_b32_e64 v159, 0, 1, s[90:91]
	s_mov_b64 s[14:15], -1
	v_cmp_ne_u32_e64 s[10:11], 1, v159
	s_waitcnt lgkmcnt(0)
	v_mfma_f32_16x16x32_bf16 v[132:135], v[168:171], v[176:179], v[132:135]
	ds_read_b128 v[168:171], v167 offset:18496
	ds_read_b128 v[172:175], v145 offset:27712
	ds_read_b128 v[176:179], v145 offset:30016
	s_andn2_b64 vcc, exec, s[90:91]
	s_waitcnt lgkmcnt(1)
	v_mfma_f32_16x16x32_bf16 v[128:131], v[168:171], v[172:175], v[128:131]
	s_waitcnt lgkmcnt(0)
	v_mfma_f32_16x16x32_bf16 v[132:135], v[168:171], v[176:179], v[132:135]
	s_cbranch_vccnz .LBB0_662
	s_mov_b64 s[14:15], 0

; #define LAS __attribute__((address_space(3)))
; __device__ __forceinline__ unsigned pk2(float lo, float hi) { const f32x2 v = {lo, hi}; const bf16x2_t b = __builtin_convertvector(v, bf16x2_t); return __builtin_bit_cast(unsigned, b); }
; __device__ __forceinline__ void ret_scan_phase(int j, LAS unsigned char* lds, int tid, int lane, int wave) { KARGS;
;     ...
;                 if (samp ? (s > 0) : (s & 1)) { const int sbp = samp ? ((s - 1) & 1) : (((s - 1) >> 1) & 1);
;                   const u32x4 vv = *(const LAS u32x4*)(lds + 2 * RS_STAGE + sbp * RS_TILE + (tid >> 3) * RS_PITCH + (tid & 7) * 16);
;                   *(u32x4*)(ST + ((size_t)((c - 1) * 8 + h) * 512 + 64 * eo + (tid >> 3)) * 256 + 64 * dq + (tid & 7) * 8) = vv; }
;                 if (samp || !(s & 1)) { const int sb = samp ? (s & 1) : ((s >> 1) & 1);
;                   LAS unsigned char* sp = lds + 2 * RS_STAGE + sb * RS_TILE + (32 * ep + fr) * RS_PITCH + (16 * dtw + 4 * fq) * 2;
;                   u32x2 p; p.x = pk2(acc0[0], acc0[1]); p.y = pk2(acc0[2], acc0[3]); *(LAS u32x2*)sp = p;
;                   p.x = pk2(acc1[0], acc1[1]); p.y = pk2(acc1[2], acc1[3]); *(LAS u32x2*)(sp + 16 * RS_PITCH) = p; }
;                 acc0 *= g64; acc1 *= g64;
;                 { const LAS unsigned char* st = lds + (c & 1) * RS_STAGE;
; #pragma unroll
;                   for (int ks = 0; ks < 2; ++ks) { const bf16x8 kf = *(const LAS bf16x8*)(st + ka_off + 64 * ks), v0 = *(const LAS bf16x8*)(st + vb_off + 64 * ks), v1 = *(const LAS bf16x8*)(st + vb_off + 16 * RS_PITCH + 64 * ks);
;                       acc0 = __builtin_amdgcn_mfma_f32_16x16x32_bf16(kf, v0, acc0, 0, 0, 0); acc1 = __builtin_amdgcn_mfma_f32_16x16x32_bf16(kf, v1, acc1, 0, 0, 0); } }
.LBB0_670:
	s_add_i32 s15, s71, 11
	s_min_u32 s15, s15, 0x7e
	s_add_i32 s15, s15, 9
	s_lshl_b32 s68, s15, 18
	s_barrier
	s_waitcnt vmcnt(16)
	ds_write_b128 v164, v[88:91]
	s_waitcnt vmcnt(15)
	ds_write_b128 v164, v[92:95] offset:9216
	v_lshl_add_u64 v[88:89], v[154:155], 0, s[68:69]
	s_lshl_b32 s68, s15, 19
	v_lshl_add_u64 v[92:93], v[156:157], 0, s[68:69]
	global_load_dwordx4 v[88:91], v[88:89], off
	s_nop 0
	global_load_dwordx4 v[92:95], v[92:93], off
	v_add_u32_e32 v159, s14, v164
	ds_read_b128 v[180:183], v159 offset:36864
	v_lshl_add_u64 v[184:185], v[146:147], 0, s[52:53]
	s_and_b64 vcc, exec, s[8:9]
	s_cbranch_vccnz .LBB0_672
	s_nop 0
	v_cvt_pk_bf16_f32 v168, v128, v129
	v_cvt_pk_bf16_f32 v169, v130, v131
	ds_write_b64 v166, v[168:169] offset:46080
	v_cvt_pk_bf16_f32 v168, v132, v133
	v_cvt_pk_bf16_f32 v169, v134, v135
	ds_write_b64 v166, v[168:169] offset:48384
.LBB0_672:
	ds_read_b128 v[168:171], v167 offset:18432
	ds_read_b128 v[172:175], v145 offset:27648
	ds_read_b128 v[176:179], v145 offset:29952
	v_mov_b32_e32 v159, v158
	v_pk_mul_f32 v[130:131], v[158:159], v[130:131]
	v_pk_mul_f32 v[128:129], v[160:161], v[128:129]
	v_pk_mul_f32 v[134:135], v[158:159], v[134:135]
	v_pk_mul_f32 v[132:133], v[160:161], v[132:133]
	s_waitcnt lgkmcnt(1)
	v_mfma_f32_16x16x32_bf16 v[128:131], v[168:171], v[172:175], v[128:131]
	global_store_dwordx4 v[184:185], v[180:183], off
	s_mov_b64 s[14:15], -1
	s_and_b64 vcc, exec, s[10:11]
	s_waitcnt lgkmcnt(0)
	v_mfma_f32_16x16x32_bf16 v[132:135], v[168:171], v[176:179], v[132:135]
	ds_read_b128 v[168:171], v167 offset:18496
	ds_read_b128 v[172:175], v145 offset:27712
	ds_read_b128 v[176:179], v145 offset:30016
	s_waitcnt lgkmcnt(1)
	v_mfma_f32_16x16x32_bf16 v[128:131], v[168:171], v[172:175], v[128:131]
	s_waitcnt lgkmcnt(0)
	v_mfma_f32_16x16x32_bf16 v[132:135], v[168:171], v[176:179], v[132:135]
	s_cbranch_vccnz .LBB0_674
	s_mov_b64 s[14:15], 0

; #define LAS __attribute__((address_space(3)))
; __device__ __forceinline__ unsigned pk2(float lo, float hi) { const f32x2 v = {lo, hi}; const bf16x2_t b = __builtin_convertvector(v, bf16x2_t); return __builtin_bit_cast(unsigned, b); }
; __device__ __forceinline__ void ret_scan_phase(int j, LAS unsigned char* lds, int tid, int lane, int wave) { KARGS;
;     ...
;                 if (samp ? (s > 0) : (s & 1)) { const int sbp = samp ? ((s - 1) & 1) : (((s - 1) >> 1) & 1);
;                   const u32x4 vv = *(const LAS u32x4*)(lds + 2 * RS_STAGE + sbp * RS_TILE + (tid >> 3) * RS_PITCH + (tid & 7) * 16);
;                   *(u32x4*)(ST + ((size_t)((c - 1) * 8 + h) * 512 + 64 * eo + (tid >> 3)) * 256 + 64 * dq + (tid & 7) * 8) = vv; }
;                 if (samp || !(s & 1)) { const int sb = samp ? (s & 1) : ((s >> 1) & 1);
;                   LAS unsigned char* sp = lds + 2 * RS_STAGE + sb * RS_TILE + (32 * ep + fr) * RS_PITCH + (16 * dtw + 4 * fq) * 2;
;                   u32x2 p; p.x = pk2(acc0[0], acc0[1]); p.y = pk2(acc0[2], acc0[3]); *(LAS u32x2*)sp = p;
;                   p.x = pk2(acc1[0], acc1[1]); p.y = pk2(acc1[2], acc1[3]); *(LAS u32x2*)(sp + 16 * RS_PITCH) = p; }
;                 acc0 *= g64; acc1 *= g64;
;                 { const LAS unsigned char* st = lds + (c & 1) * RS_STAGE;
; #pragma unroll
;                   for (int ks = 0; ks < 2; ++ks) { const bf16x8 kf = *(const LAS bf16x8*)(st + ka_off + 64 * ks), v0 = *(const LAS bf16x8*)(st + vb_off + 64 * ks), v1 = *(const LAS bf16x8*)(st + vb_off + 16 * RS_PITCH + 64 * ks);
;                       acc0 = __builtin_amdgcn_mfma_f32_16x16x32_bf16(kf, v0, acc0, 0, 0, 0); acc1 = __builtin_amdgcn_mfma_f32_16x16x32_bf16(kf, v1, acc1, 0, 0, 0); } }
.LBB0_682:
	s_add_i32 s14, s71, 13
	s_min_u32 s14, s14, 0x7e
	s_add_i32 s14, s14, 9
	s_lshl_b32 s68, s14, 18
	s_barrier
	s_waitcnt vmcnt(17)
	ds_write_b128 v164, v[104:107]
	s_waitcnt vmcnt(16)
	ds_write_b128 v164, v[108:111] offset:9216
	v_lshl_add_u64 v[104:105], v[154:155], 0, s[68:69]
	s_lshl_b32 s68, s14, 19
	v_lshl_add_u64 v[108:109], v[156:157], 0, s[68:69]
	global_load_dwordx4 v[104:107], v[104:105], off
	s_nop 0
	global_load_dwordx4 v[108:111], v[108:109], off
	ds_read_b128 v[180:183], v164 offset:36864
	s_xor_b64 s[14:15], s[6:7], -1
	v_cndmask_b32_e64 v159, 0, 1, s[14:15]
	v_lshl_add_u64 v[184:185], v[146:147], 0, s[46:47]
	v_readfirstlane_b32 s90, v159
	s_and_b64 vcc, exec, s[14:15]
	s_cbranch_vccnz .LBB0_684
	s_lshr_b32 s14, 5, s90
	s_bitcmp1_b32 s14, 0
	s_cselect_b32 s14, 0x2400, 0
	v_add_u32_e32 v159, s14, v166
	v_cvt_pk_bf16_f32 v168, v128, v129
	v_cvt_pk_bf16_f32 v169, v130, v131
	ds_write_b64 v159, v[168:169] offset:36864
	v_cvt_pk_bf16_f32 v168, v132, v133
	v_cvt_pk_bf16_f32 v169, v134, v135
	ds_write_b64 v159, v[168:169] offset:39168
.LBB0_684:
	ds_read_b128 v[168:171], v167 offset:18432
	ds_read_b128 v[172:175], v145 offset:27648
	ds_read_b128 v[176:179], v145 offset:29952
	v_mov_b32_e32 v159, v158
	v_pk_mul_f32 v[130:131], v[158:159], v[130:131]
	v_pk_mul_f32 v[128:129], v[160:161], v[128:129]
	v_pk_mul_f32 v[134:135], v[158:159], v[134:135]
	v_pk_mul_f32 v[132:133], v[160:161], v[132:133]
	s_waitcnt lgkmcnt(1)
	v_mfma_f32_16x16x32_bf16 v[128:131], v[168:171], v[172:175], v[128:131]
	global_store_dwordx4 v[184:185], v[180:183], off
	s_mov_b64 s[14:15], -1
	s_and_b64 vcc, exec, s[10:11]
	s_waitcnt lgkmcnt(0)
	v_mfma_f32_16x16x32_bf16 v[168:171], v[168:171], v[176:179], v[132:135]
	ds_read_b128 v[172:175], v167 offset:18496
	s_nop 1
	ds_read_b128 v[132:135], v145 offset:27712
	ds_read_b128 v[176:179], v145 offset:30016
	s_waitcnt lgkmcnt(1)
	v_mfma_f32_16x16x32_bf16 v[132:135], v[172:175], v[132:135], v[128:131]
	s_waitcnt lgkmcnt(0)
	v_mfma_f32_16x16x32_bf16 v[128:131], v[172:175], v[176:179], v[168:171]
	s_cbranch_vccnz .LBB0_686
	s_mov_b64 s[14:15], 0

; #define LAS __attribute__((address_space(3)))
; __device__ __forceinline__ unsigned pk2(float lo, float hi) { const f32x2 v = {lo, hi}; const bf16x2_t b = __builtin_convertvector(v, bf16x2_t); return __builtin_bit_cast(unsigned, b); }
; __device__ __forceinline__ void ret_scan_phase(int j, LAS unsigned char* lds, int tid, int lane, int wave) { KARGS;
;     ...
;                 if (samp ? (s > 0) : (s & 1)) { const int sbp = samp ? ((s - 1) & 1) : (((s - 1) >> 1) & 1);
;                   const u32x4 vv = *(const LAS u32x4*)(lds + 2 * RS_STAGE + sbp * RS_TILE + (tid >> 3) * RS_PITCH + (tid & 7) * 16);
;                   *(u32x4*)(ST + ((size_t)((c - 1) * 8 + h) * 512 + 64 * eo + (tid >> 3)) * 256 + 64 * dq + (tid & 7) * 8) = vv; }
;                 if (samp || !(s & 1)) { const int sb = samp ? (s & 1) : ((s >> 1) & 1);
;                   LAS unsigned char* sp = lds + 2 * RS_STAGE + sb * RS_TILE + (32 * ep + fr) * RS_PITCH + (16 * dtw + 4 * fq) * 2;
;                   u32x2 p; p.x = pk2(acc0[0], acc0[1]); p.y = pk2(acc0[2], acc0[3]); *(LAS u32x2*)sp = p;
;                   p.x = pk2(acc1[0], acc1[1]); p.y = pk2(acc1[2], acc1[3]); *(LAS u32x2*)(sp + 16 * RS_PITCH) = p; }
;                 acc0 *= g64; acc1 *= g64;
;                 { const LAS unsigned char* st = lds + (c & 1) * RS_STAGE;
; #pragma unroll
;                   for (int ks = 0; ks < 2; ++ks) { const bf16x8 kf = *(const LAS bf16x8*)(st + ka_off + 64 * ks), v0 = *(const LAS bf16x8*)(st + vb_off + 64 * ks), v1 = *(const LAS bf16x8*)(st + vb_off + 16 * RS_PITCH + 64 * ks);
;                       acc0 = __builtin_amdgcn_mfma_f32_16x16x32_bf16(kf, v0, acc0, 0, 0, 0); acc1 = __builtin_amdgcn_mfma_f32_16x16x32_bf16(kf, v1, acc1, 0, 0, 0); } }
;                 if (samp || c == NPC - 1) {
.LBB0_694:
	s_add_i32 s11, s71, 15
	s_min_u32 s11, s11, 0x7e
	s_add_i32 s11, s11, 9
	s_lshl_b32 s68, s11, 18
	s_barrier
	s_waitcnt vmcnt(18)
	ds_write_b128 v164, v[120:123]
	s_waitcnt vmcnt(17)
	ds_write_b128 v164, v[124:127] offset:9216
	v_lshl_add_u64 v[120:121], v[154:155], 0, s[68:69]
	s_lshl_b32 s68, s11, 19
	v_lshl_add_u64 v[124:125], v[156:157], 0, s[68:69]
	global_load_dwordx4 v[120:123], v[120:121], off
	s_nop 0
	global_load_dwordx4 v[124:127], v[124:125], off
	v_add_u32_e32 v159, s10, v164
	ds_read_b128 v[180:183], v159 offset:36864
	v_lshl_add_u64 v[184:185], v[146:147], 0, s[66:67]
	s_and_b64 vcc, exec, s[8:9]
	s_cbranch_vccnz .LBB0_696
	s_nop 0
	v_cvt_pk_bf16_f32 v168, v128, v129
	v_cvt_pk_bf16_f32 v169, v130, v131
	ds_write_b64 v166, v[168:169] offset:46080
	v_cvt_pk_bf16_f32 v168, v132, v133
	v_cvt_pk_bf16_f32 v169, v134, v135
	ds_write_b64 v166, v[168:169] offset:48384
.LBB0_696:
	ds_read_b128 v[168:171], v167 offset:18432
	ds_read_b128 v[172:175], v145 offset:27648
	ds_read_b128 v[176:179], v145 offset:29952
	v_mov_b32_e32 v159, v158
	v_pk_mul_f32 v[130:131], v[158:159], v[130:131]
	v_pk_mul_f32 v[128:129], v[160:161], v[128:129]
	v_pk_mul_f32 v[134:135], v[158:159], v[134:135]
	v_pk_mul_f32 v[132:133], v[160:161], v[132:133]
	s_waitcnt lgkmcnt(1)
	v_mfma_f32_16x16x32_bf16 v[128:131], v[168:171], v[172:175], v[128:131]
	global_store_dwordx4 v[184:185], v[180:183], off
	s_cmpk_eq_i32 s71, 0x70
	s_cselect_b64 s[8:9], -1, 0
	s_or_b64 s[10:11], s[6:7], s[8:9]
	s_waitcnt lgkmcnt(0)
	v_mfma_f32_16x16x32_bf16 v[132:135], v[168:171], v[176:179], v[132:135]
	ds_read_b128 v[168:171], v167 offset:18496
	ds_read_b128 v[172:175], v145 offset:27712
	ds_read_b128 v[176:179], v145 offset:30016
	s_mov_b64 s[8:9], -1
	s_and_b64 vcc, exec, s[10:11]
	s_waitcnt lgkmcnt(1)
	v_mfma_f32_16x16x32_bf16 v[128:131], v[168:171], v[172:175], v[128:131]
	s_waitcnt lgkmcnt(0)
	v_mfma_f32_16x16x32_bf16 v[132:135], v[168:171], v[176:179], v[132:135]
	s_cbranch_vccnz .LBB0_698
	s_mov_b64 s[8:9], 0
